# baseline (speedup 1.0000x reference)
; __device__ __forceinline__ void partialSM(f32x16& p0, f32x16& p1, float& m_reg, float& mn, float& alpha) {
;     float pmax = p0[0];
; #pragma unroll
;     for (int r = 1; r < 16; ++r) pmax = fmaxf(pmax, p0[r]);
; #pragma unroll
;     for (int r = 0; r < 16; ++r) pmax = fmaxf(pmax, p1[r]);
;     { auto rr = __builtin_amdgcn_permlane32_swap(__float_as_uint(pmax), __float_as_uint(pmax), false, false);
;       pmax = fmaxf(__uint_as_float(rr[0]), __uint_as_float(rr[1])); }
;     constexpr float C2 = 1.4426950408889634f * ASCALE;
;     if (__builtin_expect(__all((pmax - m_reg) * ASCALE <= ATHR), 1)) { mn = m_reg; alpha = 1.f; }
;     else { mn = fmaxf(m_reg, pmax); alpha = __builtin_amdgcn_exp2f((m_reg - mn) * C2); m_reg = mn; }
; template <int VB>
; __device__ __forceinline__ void pv_tile(f32x16* o, int vb0, bf16x8 pa0, bf16x8 pa1, bf16x8 pa2, bf16x8 pa3) {
;     ...
;     PV_D0(0); PV_D0(1); PV_D0(2); PV_D0(3);
.LBB0_410:
	s_nop 0
	s_waitcnt lgkmcnt(4)
	v_mfma_f32_32x32x16_bf16 v[50:65], v[166:169], v[214:217], v[50:65]
	ds_read_b64_tr_b16 v[214:215], v194 offset:0x200
	ds_read_b64_tr_b16 v[216:217], v194 offset:0xa00
	v_max_f32_e32 v0, v82, v83
	v_mfma_f32_32x32x16_bf16 v[50:65], v[170:173], v[218:221], v[50:65]
	ds_read_b64_tr_b16 v[218:219], v194 offset:0x1200
	ds_read_b64_tr_b16 v[220:221], v194 offset:0x1a00
	v_max3_f32 v0, v0, v84, v85
	v_max3_f32 v0, v0, v86, v87
	s_waitcnt lgkmcnt(4)
	v_mfma_f32_32x32x16_bf16 v[50:65], v[174:177], v[222:225], v[50:65]
	ds_read_b64_tr_b16 v[222:223], v194 offset:0x2200
	ds_read_b64_tr_b16 v[224:225], v194 offset:0x2a00
	v_max3_f32 v0, v0, v88, v89
	v_max3_f32 v0, v0, v90, v91
	v_mfma_f32_32x32x16_bf16 v[50:65], v[178:181], v[226:229], v[50:65]
	ds_read_b64_tr_b16 v[226:227], v194 offset:0x3200
	ds_read_b64_tr_b16 v[228:229], v194 offset:0x3a00
	v_max3_f32 v0, v0, v92, v93
	v_max3_f32 v0, v0, v94, v95
	v_max3_f32 v0, v0, v96, v97
	s_waitcnt lgkmcnt(4)
	v_mfma_f32_32x32x16_bf16 v[34:49], v[166:169], v[214:217], v[34:49]
	ds_read_b64_tr_b16 v[214:215], v194 offset:0x400
	ds_read_b64_tr_b16 v[216:217], v194 offset:0xc00
	v_max3_f32 v0, v0, v66, v67
	v_max3_f32 v0, v0, v68, v69
	v_mfma_f32_32x32x16_bf16 v[34:49], v[170:173], v[218:221], v[34:49]
	ds_read_b64_tr_b16 v[218:219], v194 offset:0x1400
	ds_read_b64_tr_b16 v[220:221], v194 offset:0x1c00
	v_max3_f32 v0, v0, v70, v71
	v_max3_f32 v0, v0, v72, v73
	s_waitcnt lgkmcnt(4)
	v_mfma_f32_32x32x16_bf16 v[34:49], v[174:177], v[222:225], v[34:49]
	ds_read_b64_tr_b16 v[222:223], v194 offset:0x2400
	ds_read_b64_tr_b16 v[224:225], v194 offset:0x2c00
	v_max3_f32 v0, v0, v74, v75
	v_max3_f32 v0, v0, v76, v77
	v_max3_f32 v0, v0, v78, v79
	v_mfma_f32_32x32x16_bf16 v[34:49], v[178:181], v[226:229], v[34:49]
	ds_read_b64_tr_b16 v[226:227], v194 offset:0x3400
	ds_read_b64_tr_b16 v[228:229], v194 offset:0x3c00
	v_max3_f32 v0, v0, v80, v81
	v_mov_b32_e32 v190, v0
	s_waitcnt lgkmcnt(4)
	v_mfma_f32_32x32x16_bf16 v[18:33], v[166:169], v[214:217], v[18:33]
	ds_read_b64_tr_b16 v[214:215], v194 offset:0x600
	ds_read_b64_tr_b16 v[216:217], v194 offset:0xe00
	v_permlane32_swap_b32_e32 v0, v190
	v_mfma_f32_32x32x16_bf16 v[18:33], v[170:173], v[218:221], v[18:33]
	ds_read_b64_tr_b16 v[218:219], v194 offset:0x1600
	ds_read_b64_tr_b16 v[220:221], v194 offset:0x1e00
	v_max_f32_e32 v0, v0, v190
	s_waitcnt lgkmcnt(4)
	v_mfma_f32_32x32x16_bf16 v[18:33], v[174:177], v[222:225], v[18:33]
	ds_read_b64_tr_b16 v[222:223], v194 offset:0x2600
	ds_read_b64_tr_b16 v[224:225], v194 offset:0x2e00
	v_sub_f32_e32 v190, v0, v210
	v_mfma_f32_32x32x16_bf16 v[18:33], v[178:181], v[226:229], v[18:33]
	ds_read_b64_tr_b16 v[226:227], v194 offset:0x3600
	ds_read_b64_tr_b16 v[228:229], v194 offset:0x3e00
	v_max_f32_e32 v0, v210, v0
	v_sub_f32_e32 v191, v210, v0
	s_waitcnt lgkmcnt(4)
	v_mfma_f32_32x32x16_bf16 v[2:17], v[166:169], v[214:217], v[2:17]
	s_waitcnt vmcnt(2)
	v_add_u32_e32 v192, 0x10800, v206
	ds_write_b128 v207, v[154:157] offset:32768
	ds_write_b128 v207, v[158:161] offset:41472
	ds_write_b128 v192, v[162:165]
	v_mul_f32_e32 v191, 0x3dd53b94, v191
	v_mul_f32_e32 v190, 0x3d93cd3a, v190
	v_exp_f32_e32 v191, v191
	v_mfma_f32_32x32x16_bf16 v[2:17], v[170:173], v[218:221], v[2:17]
	s_mov_b32 s6, 0x41000000
	v_cmp_ge_f32_e32 vcc, s6, v190
	s_waitcnt lgkmcnt(3)
	v_mfma_f32_32x32x16_bf16 v[2:17], v[174:177], v[222:225], v[2:17]
	s_cmp_eq_u64 vcc, exec
	s_cselect_b64 s[6:7], -1, 0
	v_mfma_f32_32x32x16_bf16 v[2:17], v[178:181], v[226:229], v[2:17]
	s_barrier
	s_waitcnt vmcnt(0)
	v_cndmask_b32_e64 v213, v191, 1.0, s[6:7]
	v_cmp_gt_f32_e32 vcc, 1.0, v213
	ds_write_b128 v202, v[146:149]
	ds_write_b128 v203, v[150:153]
	s_cbranch_vccz .LBB0_414
	s_and_saveexec_b64 s[8:9], s[4:5]
	ds_write_b32 v195, v213 offset:128
	s_or_b64 exec, exec, s[8:9]
	s_waitcnt lgkmcnt(0)
	ds_read_b128 v[166:169], v198 offset:224
	ds_read_b128 v[170:173], v198 offset:192
	ds_read_b128 v[174:177], v198 offset:160
	ds_read_b128 v[178:181], v198 offset:128
	s_waitcnt lgkmcnt(3)
	v_pk_mul_f32 v[64:65], v[64:65], v[168:169]
	s_waitcnt lgkmcnt(2)
	v_pk_mul_f32 v[60:61], v[60:61], v[172:173]
	s_waitcnt lgkmcnt(1)
	v_pk_mul_f32 v[56:57], v[56:57], v[176:177]
	s_waitcnt lgkmcnt(0)
	v_pk_mul_f32 v[52:53], v[52:53], v[180:181]
	v_pk_mul_f32 v[62:63], v[62:63], v[166:167]
	v_pk_mul_f32 v[58:59], v[58:59], v[170:171]
	v_pk_mul_f32 v[54:55], v[54:55], v[174:175]
	v_pk_mul_f32 v[50:51], v[50:51], v[178:179]
	v_pk_mul_f32 v[48:49], v[48:49], v[168:169]
	v_pk_mul_f32 v[44:45], v[44:45], v[172:173]
	v_pk_mul_f32 v[40:41], v[40:41], v[176:177]
	v_pk_mul_f32 v[36:37], v[36:37], v[180:181]
	v_pk_mul_f32 v[46:47], v[46:47], v[166:167]
	v_pk_mul_f32 v[42:43], v[42:43], v[170:171]
	v_pk_mul_f32 v[38:39], v[38:39], v[174:175]
	v_pk_mul_f32 v[34:35], v[34:35], v[178:179]
	v_pk_mul_f32 v[32:33], v[32:33], v[168:169]
	v_pk_mul_f32 v[28:29], v[28:29], v[172:173]
	v_pk_mul_f32 v[24:25], v[24:25], v[176:177]
	v_pk_mul_f32 v[20:21], v[20:21], v[180:181]
	v_pk_mul_f32 v[30:31], v[30:31], v[166:167]
	v_pk_mul_f32 v[26:27], v[26:27], v[170:171]
	v_pk_mul_f32 v[22:23], v[22:23], v[174:175]
	v_pk_mul_f32 v[18:19], v[18:19], v[178:179]
	v_pk_mul_f32 v[16:17], v[16:17], v[168:169]
	v_pk_mul_f32 v[12:13], v[12:13], v[172:173]
	v_pk_mul_f32 v[8:9], v[8:9], v[176:177]
	v_pk_mul_f32 v[4:5], v[4:5], v[180:181]
	v_pk_mul_f32 v[14:15], v[14:15], v[166:167]
	v_pk_mul_f32 v[10:11], v[10:11], v[170:171]
	v_pk_mul_f32 v[6:7], v[6:7], v[174:175]
	v_pk_mul_f32 v[2:3], v[2:3], v[178:179]

; __device__ __forceinline__ void partialSM(f32x16& p0, f32x16& p1, float& m_reg, float& mn, float& alpha) {
;     float pmax = p0[0];
; #pragma unroll
;     for (int r = 1; r < 16; ++r) pmax = fmaxf(pmax, p0[r]);
; #pragma unroll
;     for (int r = 0; r < 16; ++r) pmax = fmaxf(pmax, p1[r]);
;     { auto rr = __builtin_amdgcn_permlane32_swap(__float_as_uint(pmax), __float_as_uint(pmax), false, false);
;       pmax = fmaxf(__uint_as_float(rr[0]), __uint_as_float(rr[1])); }
; template <int VB>
; __device__ __forceinline__ void pv_tile(f32x16* o, int vb0, bf16x8 pa0, bf16x8 pa1, bf16x8 pa2, bf16x8 pa3) {
;     ...
;     PV_D0(0); PV_D0(1); PV_D0(2); PV_D0(3);
.LBB0_418:
	s_nop 0
	s_waitcnt lgkmcnt(4)
	v_mfma_f32_32x32x16_bf16 v[50:65], v[166:169], v[218:221], v[50:65]
	ds_read_b64_tr_b16 v[218:219], v194 offset:0x4200
	ds_read_b64_tr_b16 v[220:221], v194 offset:0x4a00
	v_mfma_f32_32x32x16_bf16 v[50:65], v[170:173], v[222:225], v[50:65]
	ds_read_b64_tr_b16 v[222:223], v194 offset:0x5200
	ds_read_b64_tr_b16 v[224:225], v194 offset:0x5a00
	v_max_f32_e32 v0, v82, v83
	v_max3_f32 v0, v0, v84, v85
	s_waitcnt lgkmcnt(4)
	v_mfma_f32_32x32x16_bf16 v[50:65], v[174:177], v[226:229], v[50:65]
	ds_read_b64_tr_b16 v[226:227], v194 offset:0x6200
	ds_read_b64_tr_b16 v[228:229], v194 offset:0x6a00
	v_max3_f32 v0, v0, v86, v87
	v_max3_f32 v0, v0, v88, v89
	v_mfma_f32_32x32x16_bf16 v[50:65], v[178:181], v[230:233], v[50:65]
	ds_read_b64_tr_b16 v[230:231], v194 offset:0x7200
	ds_read_b64_tr_b16 v[232:233], v194 offset:0x7a00
	v_max3_f32 v0, v0, v90, v91
	v_max3_f32 v0, v0, v92, v93
	s_waitcnt lgkmcnt(4)
	v_mfma_f32_32x32x16_bf16 v[34:49], v[166:169], v[218:221], v[34:49]
	ds_read_b64_tr_b16 v[218:219], v194 offset:0x4400
	ds_read_b64_tr_b16 v[220:221], v194 offset:0x4c00
	v_max3_f32 v0, v0, v94, v95
	v_max3_f32 v0, v0, v96, v97
	v_mfma_f32_32x32x16_bf16 v[34:49], v[170:173], v[222:225], v[34:49]
	ds_read_b64_tr_b16 v[222:223], v194 offset:0x5400
	ds_read_b64_tr_b16 v[224:225], v194 offset:0x5c00
	v_max3_f32 v0, v0, v66, v67
	v_max3_f32 v0, v0, v68, v69
	s_waitcnt lgkmcnt(4)
	v_mfma_f32_32x32x16_bf16 v[34:49], v[174:177], v[226:229], v[34:49]
	ds_read_b64_tr_b16 v[226:227], v194 offset:0x6400
	ds_read_b64_tr_b16 v[228:229], v194 offset:0x6c00
	v_max3_f32 v0, v0, v70, v71
	v_max3_f32 v0, v0, v72, v73
	v_mfma_f32_32x32x16_bf16 v[34:49], v[178:181], v[230:233], v[34:49]
	ds_read_b64_tr_b16 v[230:231], v194 offset:0x7400
	ds_read_b64_tr_b16 v[232:233], v194 offset:0x7c00
	v_max3_f32 v0, v0, v74, v75
	v_max3_f32 v0, v0, v76, v77
	s_waitcnt lgkmcnt(4)
	v_mfma_f32_32x32x16_bf16 v[18:33], v[166:169], v[218:221], v[18:33]
	ds_read_b64_tr_b16 v[218:219], v194 offset:0x4600
	ds_read_b64_tr_b16 v[220:221], v194 offset:0x4e00
	v_max3_f32 v0, v0, v78, v79
	v_max3_f32 v0, v0, v80, v81
	v_mfma_f32_32x32x16_bf16 v[18:33], v[170:173], v[222:225], v[18:33]
	ds_read_b64_tr_b16 v[222:223], v194 offset:0x5600
	ds_read_b64_tr_b16 v[224:225], v194 offset:0x5e00
	v_mov_b32_e32 v190, v0
	s_waitcnt lgkmcnt(4)
	v_mfma_f32_32x32x16_bf16 v[18:33], v[174:177], v[226:229], v[18:33]
	ds_read_b64_tr_b16 v[226:227], v194 offset:0x6600
	ds_read_b64_tr_b16 v[228:229], v194 offset:0x6e00
	v_permlane32_swap_b32_e32 v0, v190
	v_mfma_f32_32x32x16_bf16 v[18:33], v[178:181], v[230:233], v[18:33]
	ds_read_b64_tr_b16 v[230:231], v194 offset:0x7600
	ds_read_b64_tr_b16 v[232:233], v194 offset:0x7e00
	v_max_f32_e32 v0, v0, v190
	s_waitcnt lgkmcnt(4)
	v_mfma_f32_32x32x16_bf16 v[2:17], v[166:169], v[218:221], v[2:17]
	s_and_b64 vcc, exec, s[90:91]
	s_cbranch_vccnz .Lkw2_do
	s_waitcnt lgkmcnt(0)
	s_branch .Lkw2_done

; template <int VB>
; __device__ __forceinline__ void pv_tile(f32x16* o, int vb0, bf16x8 pa0, bf16x8 pa1, bf16x8 pa2, bf16x8 pa3) {
;     ...
;     PV_D0(0); PV_D0(1); PV_D0(2); PV_D0(3);
.Lkw2_done:
	v_sub_f32_e32 v190, v0, v210
	v_mul_f32_e32 v190, 0x3d93cd3a, v190
	v_mfma_f32_32x32x16_bf16 v[2:17], v[170:173], v[222:225], v[2:17]
	s_mov_b32 s6, 0x41000000
	v_cmp_ge_f32_e32 vcc, s6, v190
	s_waitcnt lgkmcnt(3)
	v_mfma_f32_32x32x16_bf16 v[2:17], v[174:177], v[226:229], v[2:17]
	s_cmp_eq_u64 vcc, exec
	s_cselect_b64 s[6:7], -1, 0
	v_mfma_f32_32x32x16_bf16 v[2:17], v[178:181], v[230:233], v[2:17]
	s_andn2_b64 vcc, exec, s[90:91]
	s_barrier
	s_cbranch_vccnz .LBB0_420
	s_waitcnt vmcnt(0)
	ds_write_b128 v202, v[146:149] offset:16384
	s_waitcnt vmcnt(0)
	ds_write_b128 v203, v[150:153] offset:16384
